# GEMM K-loops: barrier at MFMA group 11 (right after the last read of the current buffer), A-first DMA order
# speedup vs baseline: 1.0093x; 1.0010x over previous
.LBB0_203:
	ds_read_b128 v[226:229], v157
	ds_read_b128 v[230:233], v158
	ds_read_b128 v[234:237], v159
	s_waitcnt lgkmcnt(5)
	v_mfma_f32_16x16x32_bf16 v[124:127], v[214:217], v[174:177], v[124:127]
	v_mfma_f32_16x16x32_bf16 v[120:123], v[214:217], v[178:181], v[120:123]
	v_mfma_f32_16x16x32_bf16 v[116:119], v[214:217], v[182:185], v[116:119]
	v_mfma_f32_16x16x32_bf16 v[112:115], v[214:217], v[186:189], v[112:115]
	ds_read_b128 v[238:241], v160
	s_waitcnt lgkmcnt(5)
	v_mfma_f32_16x16x32_bf16 v[108:111], v[218:221], v[174:177], v[108:111]
	v_mfma_f32_16x16x32_bf16 v[104:107], v[218:221], v[178:181], v[104:107]
	v_mfma_f32_16x16x32_bf16 v[100:103], v[218:221], v[182:185], v[100:103]
	v_mfma_f32_16x16x32_bf16 v[96:99], v[218:221], v[186:189], v[96:99]
	ds_read_b128 v[242:245], v161
	ds_read_b128 v[190:193], v153 offset:33792
	s_waitcnt lgkmcnt(6)
	v_mfma_f32_16x16x32_bf16 v[92:95], v[222:225], v[174:177], v[92:95]
	v_mfma_f32_16x16x32_bf16 v[88:91], v[222:225], v[178:181], v[88:91]
	v_mfma_f32_16x16x32_bf16 v[84:87], v[222:225], v[182:185], v[84:87]
	v_mfma_f32_16x16x32_bf16 v[80:83], v[222:225], v[186:189], v[80:83]
	ds_read_b128 v[214:217], v154 offset:1024
	ds_read_b128 v[194:197], v153 offset:35840
	s_waitcnt lgkmcnt(7)
	v_mfma_f32_16x16x32_bf16 v[76:79], v[226:229], v[174:177], v[76:79]
	v_mfma_f32_16x16x32_bf16 v[72:75], v[226:229], v[178:181], v[72:75]
	v_mfma_f32_16x16x32_bf16 v[68:71], v[226:229], v[182:185], v[68:71]
	v_mfma_f32_16x16x32_bf16 v[64:67], v[226:229], v[186:189], v[64:67]
	ds_read_b128 v[218:221], v155 offset:1024
	ds_read_b128 v[198:201], v153 offset:37888
	s_waitcnt lgkmcnt(8)
	v_mfma_f32_16x16x32_bf16 v[60:63], v[230:233], v[174:177], v[60:63]
	v_mfma_f32_16x16x32_bf16 v[56:59], v[230:233], v[178:181], v[56:59]
	v_mfma_f32_16x16x32_bf16 v[52:55], v[230:233], v[182:185], v[52:55]
	v_mfma_f32_16x16x32_bf16 v[48:51], v[230:233], v[186:189], v[48:51]
	ds_read_b128 v[222:225], v156 offset:1024
	ds_read_b128 v[210:213], v153 offset:39936
	s_waitcnt lgkmcnt(9)
	v_mfma_f32_16x16x32_bf16 v[44:47], v[234:237], v[174:177], v[44:47]
	v_mfma_f32_16x16x32_bf16 v[40:43], v[234:237], v[178:181], v[40:43]
	v_mfma_f32_16x16x32_bf16 v[36:39], v[234:237], v[182:185], v[36:39]
	v_mfma_f32_16x16x32_bf16 v[32:35], v[234:237], v[186:189], v[32:35]
	ds_read_b128 v[226:229], v157 offset:1024
	s_waitcnt lgkmcnt(9)
	v_mfma_f32_16x16x32_bf16 v[28:31], v[238:241], v[174:177], v[28:31]
	v_mfma_f32_16x16x32_bf16 v[24:27], v[238:241], v[178:181], v[24:27]
	v_mfma_f32_16x16x32_bf16 v[20:23], v[238:241], v[182:185], v[20:23]
	v_mfma_f32_16x16x32_bf16 v[16:19], v[238:241], v[186:189], v[16:19]
	ds_read_b128 v[230:233], v158 offset:1024
	s_waitcnt lgkmcnt(9)
	v_mfma_f32_16x16x32_bf16 v[12:15], v[242:245], v[174:177], v[12:15]
	v_mfma_f32_16x16x32_bf16 v[8:11], v[242:245], v[178:181], v[8:11]
	v_mfma_f32_16x16x32_bf16 v[4:7], v[242:245], v[182:185], v[4:7]
	v_mfma_f32_16x16x32_bf16 v[0:3], v[242:245], v[186:189], v[0:3]
	ds_read_b128 v[234:237], v159 offset:1024
	s_waitcnt lgkmcnt(3)
	v_mfma_f32_16x16x32_bf16 v[124:127], v[214:217], v[190:193], v[124:127]
	v_mfma_f32_16x16x32_bf16 v[120:123], v[214:217], v[194:197], v[120:123]
	v_mfma_f32_16x16x32_bf16 v[116:119], v[214:217], v[198:201], v[116:119]
	v_mfma_f32_16x16x32_bf16 v[112:115], v[214:217], v[210:213], v[112:115]
	ds_read_b128 v[238:241], v160 offset:1024
	v_mfma_f32_16x16x32_bf16 v[108:111], v[218:221], v[190:193], v[108:111]
	v_mfma_f32_16x16x32_bf16 v[104:107], v[218:221], v[194:197], v[104:107]
	v_mfma_f32_16x16x32_bf16 v[100:103], v[218:221], v[198:201], v[100:103]
	v_mfma_f32_16x16x32_bf16 v[96:99], v[218:221], v[210:213], v[96:99]
	ds_read_b128 v[242:245], v161 offset:1024
	v_mfma_f32_16x16x32_bf16 v[92:95], v[222:225], v[190:193], v[92:95]
	v_mfma_f32_16x16x32_bf16 v[88:91], v[222:225], v[194:197], v[88:91]
	v_mfma_f32_16x16x32_bf16 v[84:87], v[222:225], v[198:201], v[84:87]
	v_mfma_f32_16x16x32_bf16 v[80:83], v[222:225], v[210:213], v[80:83]
	s_waitcnt lgkmcnt(0)
	s_waitcnt vmcnt(0)
	s_barrier
	ds_read_b128 v[174:177], v162 offset:32768
	ds_read_b128 v[178:181], v162 offset:34816
	ds_read_b128 v[182:185], v162 offset:36864
	ds_read_b128 v[186:189], v162 offset:38912
	ds_read_b128 v[214:217], v170
	ds_read_b128 v[218:221], v171
	ds_read_b128 v[222:225], v163
	s_cmp_gt_u32 s23, 13
	s_cbranch_scc1 .Lg1_nostage0
	s_add_u32 m0, s24, 0x0
	v_mfma_f32_16x16x32_bf16 v[76:79], v[226:229], v[190:193], v[76:79]
	global_load_lds_dwordx4 v246, s[98:99]
	s_add_u32 m0, s24, 0x2000
	v_mfma_f32_16x16x32_bf16 v[72:75], v[226:229], v[194:197], v[72:75]
	global_load_lds_dwordx4 v247, s[98:99]
	v_mfma_f32_16x16x32_bf16 v[68:71], v[226:229], v[198:201], v[68:71]
	v_mfma_f32_16x16x32_bf16 v[64:67], v[226:229], v[210:213], v[64:67]
	s_add_u32 m0, s24, 0x4000
	v_mfma_f32_16x16x32_bf16 v[60:63], v[230:233], v[190:193], v[60:63]
	global_load_lds_dwordx4 v248, s[98:99]
	s_add_u32 m0, s24, 0x6000
	v_mfma_f32_16x16x32_bf16 v[56:59], v[230:233], v[194:197], v[56:59]
	global_load_lds_dwordx4 v249, s[98:99]
	v_mfma_f32_16x16x32_bf16 v[52:55], v[230:233], v[198:201], v[52:55]
	v_mfma_f32_16x16x32_bf16 v[48:51], v[230:233], v[210:213], v[48:51]
	s_add_u32 m0, s24, 0x8000
	v_mfma_f32_16x16x32_bf16 v[44:47], v[234:237], v[190:193], v[44:47]
	global_load_lds_dwordx4 v246, s[100:101]
	s_add_u32 m0, s24, 0xa000
	v_mfma_f32_16x16x32_bf16 v[40:43], v[234:237], v[194:197], v[40:43]
	global_load_lds_dwordx4 v247, s[100:101]
	v_mfma_f32_16x16x32_bf16 v[36:39], v[234:237], v[198:201], v[36:39]
	v_mfma_f32_16x16x32_bf16 v[32:35], v[234:237], v[210:213], v[32:35]
	s_add_u32 m0, s24, 0xc000
	v_mfma_f32_16x16x32_bf16 v[28:31], v[238:241], v[190:193], v[28:31]
	global_load_lds_dwordx4 v248, s[100:101]
	s_add_u32 m0, s24, 0xe000
	v_mfma_f32_16x16x32_bf16 v[24:27], v[238:241], v[194:197], v[24:27]
	global_load_lds_dwordx4 v249, s[100:101]
	v_mfma_f32_16x16x32_bf16 v[20:23], v[238:241], v[198:201], v[20:23]
	v_mfma_f32_16x16x32_bf16 v[16:19], v[238:241], v[210:213], v[16:19]
	v_mfma_f32_16x16x32_bf16 v[12:15], v[242:245], v[190:193], v[12:15]
	v_mfma_f32_16x16x32_bf16 v[8:11], v[242:245], v[194:197], v[8:11]
	v_mfma_f32_16x16x32_bf16 v[4:7], v[242:245], v[198:201], v[4:7]
	v_mfma_f32_16x16x32_bf16 v[0:3], v[242:245], v[210:213], v[0:3]
	s_add_u32 s98, s98, 0x80
	s_addc_u32 s99, s99, 0
	s_add_u32 s100, s100, 0x80
	s_addc_u32 s101, s101, 0
	s_branch .Lg1_half1
.Lg1_nostage0:
	v_mfma_f32_16x16x32_bf16 v[76:79], v[226:229], v[190:193], v[76:79]
	v_mfma_f32_16x16x32_bf16 v[72:75], v[226:229], v[194:197], v[72:75]
	v_mfma_f32_16x16x32_bf16 v[68:71], v[226:229], v[198:201], v[68:71]
	v_mfma_f32_16x16x32_bf16 v[64:67], v[226:229], v[210:213], v[64:67]
	v_mfma_f32_16x16x32_bf16 v[60:63], v[230:233], v[190:193], v[60:63]
	v_mfma_f32_16x16x32_bf16 v[56:59], v[230:233], v[194:197], v[56:59]
	v_mfma_f32_16x16x32_bf16 v[52:55], v[230:233], v[198:201], v[52:55]
	v_mfma_f32_16x16x32_bf16 v[48:51], v[230:233], v[210:213], v[48:51]
	v_mfma_f32_16x16x32_bf16 v[44:47], v[234:237], v[190:193], v[44:47]
	v_mfma_f32_16x16x32_bf16 v[40:43], v[234:237], v[194:197], v[40:43]
	v_mfma_f32_16x16x32_bf16 v[36:39], v[234:237], v[198:201], v[36:39]
	v_mfma_f32_16x16x32_bf16 v[32:35], v[234:237], v[210:213], v[32:35]
	v_mfma_f32_16x16x32_bf16 v[28:31], v[238:241], v[190:193], v[28:31]
	v_mfma_f32_16x16x32_bf16 v[24:27], v[238:241], v[194:197], v[24:27]
	v_mfma_f32_16x16x32_bf16 v[20:23], v[238:241], v[198:201], v[20:23]
	v_mfma_f32_16x16x32_bf16 v[16:19], v[238:241], v[210:213], v[16:19]
	v_mfma_f32_16x16x32_bf16 v[12:15], v[242:245], v[190:193], v[12:15]
	v_mfma_f32_16x16x32_bf16 v[8:11], v[242:245], v[194:197], v[8:11]
	v_mfma_f32_16x16x32_bf16 v[4:7], v[242:245], v[198:201], v[4:7]
	v_mfma_f32_16x16x32_bf16 v[0:3], v[242:245], v[210:213], v[0:3]
.Lg1_half1:
	ds_read_b128 v[226:229], v164
	ds_read_b128 v[230:233], v165
	ds_read_b128 v[234:237], v166
	s_waitcnt lgkmcnt(5)
	v_mfma_f32_16x16x32_bf16 v[124:127], v[214:217], v[174:177], v[124:127]
	v_mfma_f32_16x16x32_bf16 v[120:123], v[214:217], v[178:181], v[120:123]
	v_mfma_f32_16x16x32_bf16 v[116:119], v[214:217], v[182:185], v[116:119]
	v_mfma_f32_16x16x32_bf16 v[112:115], v[214:217], v[186:189], v[112:115]
	ds_read_b128 v[238:241], v167
	s_waitcnt lgkmcnt(5)
	v_mfma_f32_16x16x32_bf16 v[108:111], v[218:221], v[174:177], v[108:111]
	v_mfma_f32_16x16x32_bf16 v[104:107], v[218:221], v[178:181], v[104:107]
	v_mfma_f32_16x16x32_bf16 v[100:103], v[218:221], v[182:185], v[100:103]
	v_mfma_f32_16x16x32_bf16 v[96:99], v[218:221], v[186:189], v[96:99]
	ds_read_b128 v[242:245], v168
	ds_read_b128 v[190:193], v162 offset:33792
	s_waitcnt lgkmcnt(6)
	v_mfma_f32_16x16x32_bf16 v[92:95], v[222:225], v[174:177], v[92:95]
	v_mfma_f32_16x16x32_bf16 v[88:91], v[222:225], v[178:181], v[88:91]
	v_mfma_f32_16x16x32_bf16 v[84:87], v[222:225], v[182:185], v[84:87]
	v_mfma_f32_16x16x32_bf16 v[80:83], v[222:225], v[186:189], v[80:83]
	ds_read_b128 v[214:217], v170 offset:1024
	ds_read_b128 v[194:197], v162 offset:35840
	s_waitcnt lgkmcnt(7)
	v_mfma_f32_16x16x32_bf16 v[76:79], v[226:229], v[174:177], v[76:79]
	v_mfma_f32_16x16x32_bf16 v[72:75], v[226:229], v[178:181], v[72:75]
	v_mfma_f32_16x16x32_bf16 v[68:71], v[226:229], v[182:185], v[68:71]
	v_mfma_f32_16x16x32_bf16 v[64:67], v[226:229], v[186:189], v[64:67]
	ds_read_b128 v[218:221], v171 offset:1024
	ds_read_b128 v[198:201], v162 offset:37888
	s_waitcnt lgkmcnt(8)
	v_mfma_f32_16x16x32_bf16 v[60:63], v[230:233], v[174:177], v[60:63]
	v_mfma_f32_16x16x32_bf16 v[56:59], v[230:233], v[178:181], v[56:59]
	v_mfma_f32_16x16x32_bf16 v[52:55], v[230:233], v[182:185], v[52:55]
	v_mfma_f32_16x16x32_bf16 v[48:51], v[230:233], v[186:189], v[48:51]
	ds_read_b128 v[222:225], v163 offset:1024
	ds_read_b128 v[210:213], v162 offset:39936
	s_waitcnt lgkmcnt(9)
	v_mfma_f32_16x16x32_bf16 v[44:47], v[234:237], v[174:177], v[44:47]
	v_mfma_f32_16x16x32_bf16 v[40:43], v[234:237], v[178:181], v[40:43]
	v_mfma_f32_16x16x32_bf16 v[36:39], v[234:237], v[182:185], v[36:39]
	v_mfma_f32_16x16x32_bf16 v[32:35], v[234:237], v[186:189], v[32:35]
	ds_read_b128 v[226:229], v164 offset:1024
	s_waitcnt lgkmcnt(9)
	v_mfma_f32_16x16x32_bf16 v[28:31], v[238:241], v[174:177], v[28:31]
	v_mfma_f32_16x16x32_bf16 v[24:27], v[238:241], v[178:181], v[24:27]
	v_mfma_f32_16x16x32_bf16 v[20:23], v[238:241], v[182:185], v[20:23]
	v_mfma_f32_16x16x32_bf16 v[16:19], v[238:241], v[186:189], v[16:19]
	ds_read_b128 v[230:233], v165 offset:1024
	s_waitcnt lgkmcnt(9)
	v_mfma_f32_16x16x32_bf16 v[12:15], v[242:245], v[174:177], v[12:15]
	v_mfma_f32_16x16x32_bf16 v[8:11], v[242:245], v[178:181], v[8:11]
	v_mfma_f32_16x16x32_bf16 v[4:7], v[242:245], v[182:185], v[4:7]
	v_mfma_f32_16x16x32_bf16 v[0:3], v[242:245], v[186:189], v[0:3]
	ds_read_b128 v[234:237], v166 offset:1024
	s_waitcnt lgkmcnt(3)
	v_mfma_f32_16x16x32_bf16 v[124:127], v[214:217], v[190:193], v[124:127]
	v_mfma_f32_16x16x32_bf16 v[120:123], v[214:217], v[194:197], v[120:123]
	v_mfma_f32_16x16x32_bf16 v[116:119], v[214:217], v[198:201], v[116:119]
	v_mfma_f32_16x16x32_bf16 v[112:115], v[214:217], v[210:213], v[112:115]
	ds_read_b128 v[238:241], v167 offset:1024
	v_mfma_f32_16x16x32_bf16 v[108:111], v[218:221], v[190:193], v[108:111]
	v_mfma_f32_16x16x32_bf16 v[104:107], v[218:221], v[194:197], v[104:107]
	v_mfma_f32_16x16x32_bf16 v[100:103], v[218:221], v[198:201], v[100:103]
	v_mfma_f32_16x16x32_bf16 v[96:99], v[218:221], v[210:213], v[96:99]
	ds_read_b128 v[242:245], v168 offset:1024
	v_mfma_f32_16x16x32_bf16 v[92:95], v[222:225], v[190:193], v[92:95]
	v_mfma_f32_16x16x32_bf16 v[88:91], v[222:225], v[194:197], v[88:91]
	v_mfma_f32_16x16x32_bf16 v[84:87], v[222:225], v[198:201], v[84:87]
	v_mfma_f32_16x16x32_bf16 v[80:83], v[222:225], v[210:213], v[80:83]
	s_waitcnt lgkmcnt(0)
	s_waitcnt vmcnt(0)
	s_barrier
	s_cmp_gt_u32 s23, 13
	s_cbranch_scc1 .Lg1_last
	ds_read_b128 v[174:177], v153 offset:32768
	ds_read_b128 v[178:181], v153 offset:34816
	ds_read_b128 v[182:185], v153 offset:36864
	ds_read_b128 v[186:189], v153 offset:38912
	ds_read_b128 v[214:217], v154
	ds_read_b128 v[218:221], v155
	ds_read_b128 v[222:225], v156
	s_add_u32 m0, s24, 0x10400
	v_mfma_f32_16x16x32_bf16 v[76:79], v[226:229], v[190:193], v[76:79]
	global_load_lds_dwordx4 v246, s[98:99]
	s_add_u32 m0, s24, 0x12400
	v_mfma_f32_16x16x32_bf16 v[72:75], v[226:229], v[194:197], v[72:75]
	global_load_lds_dwordx4 v247, s[98:99]
	v_mfma_f32_16x16x32_bf16 v[68:71], v[226:229], v[198:201], v[68:71]
	v_mfma_f32_16x16x32_bf16 v[64:67], v[226:229], v[210:213], v[64:67]
	s_add_u32 m0, s24, 0x14400
	v_mfma_f32_16x16x32_bf16 v[60:63], v[230:233], v[190:193], v[60:63]
	global_load_lds_dwordx4 v248, s[98:99]
	s_add_u32 m0, s24, 0x16400
	v_mfma_f32_16x16x32_bf16 v[56:59], v[230:233], v[194:197], v[56:59]
	global_load_lds_dwordx4 v249, s[98:99]
	v_mfma_f32_16x16x32_bf16 v[52:55], v[230:233], v[198:201], v[52:55]
	v_mfma_f32_16x16x32_bf16 v[48:51], v[230:233], v[210:213], v[48:51]
	s_add_u32 m0, s24, 0x18400
	v_mfma_f32_16x16x32_bf16 v[44:47], v[234:237], v[190:193], v[44:47]
	global_load_lds_dwordx4 v246, s[100:101]
	s_add_u32 m0, s24, 0x1a400
	v_mfma_f32_16x16x32_bf16 v[40:43], v[234:237], v[194:197], v[40:43]
	global_load_lds_dwordx4 v247, s[100:101]
	v_mfma_f32_16x16x32_bf16 v[36:39], v[234:237], v[198:201], v[36:39]
	v_mfma_f32_16x16x32_bf16 v[32:35], v[234:237], v[210:213], v[32:35]
	s_add_u32 m0, s24, 0x1c400
	v_mfma_f32_16x16x32_bf16 v[28:31], v[238:241], v[190:193], v[28:31]
	global_load_lds_dwordx4 v248, s[100:101]
	s_add_u32 m0, s24, 0x1e400
	v_mfma_f32_16x16x32_bf16 v[24:27], v[238:241], v[194:197], v[24:27]
	global_load_lds_dwordx4 v249, s[100:101]
	v_mfma_f32_16x16x32_bf16 v[20:23], v[238:241], v[198:201], v[20:23]
	v_mfma_f32_16x16x32_bf16 v[16:19], v[238:241], v[210:213], v[16:19]
	v_mfma_f32_16x16x32_bf16 v[12:15], v[242:245], v[190:193], v[12:15]
	v_mfma_f32_16x16x32_bf16 v[8:11], v[242:245], v[194:197], v[8:11]
	v_mfma_f32_16x16x32_bf16 v[4:7], v[242:245], v[198:201], v[4:7]
	v_mfma_f32_16x16x32_bf16 v[0:3], v[242:245], v[210:213], v[0:3]
	s_add_u32 s98, s98, 0x80
	s_addc_u32 s99, s99, 0
	s_add_u32 s100, s100, 0x80
	s_addc_u32 s101, s101, 0
	s_add_i32 s23, s23, 2
	s_branch .LBB0_203
.Lg1_last:
	v_mfma_f32_16x16x32_bf16 v[76:79], v[226:229], v[190:193], v[76:79]
	v_mfma_f32_16x16x32_bf16 v[72:75], v[226:229], v[194:197], v[72:75]
	v_mfma_f32_16x16x32_bf16 v[68:71], v[226:229], v[198:201], v[68:71]
	v_mfma_f32_16x16x32_bf16 v[64:67], v[226:229], v[210:213], v[64:67]
	v_mfma_f32_16x16x32_bf16 v[60:63], v[230:233], v[190:193], v[60:63]
	v_mfma_f32_16x16x32_bf16 v[56:59], v[230:233], v[194:197], v[56:59]
	v_mfma_f32_16x16x32_bf16 v[52:55], v[230:233], v[198:201], v[52:55]
	v_mfma_f32_16x16x32_bf16 v[48:51], v[230:233], v[210:213], v[48:51]
	v_mfma_f32_16x16x32_bf16 v[44:47], v[234:237], v[190:193], v[44:47]
	v_mfma_f32_16x16x32_bf16 v[40:43], v[234:237], v[194:197], v[40:43]
	v_mfma_f32_16x16x32_bf16 v[36:39], v[234:237], v[198:201], v[36:39]
	v_mfma_f32_16x16x32_bf16 v[32:35], v[234:237], v[210:213], v[32:35]
	v_mfma_f32_16x16x32_bf16 v[28:31], v[238:241], v[190:193], v[28:31]
	v_mfma_f32_16x16x32_bf16 v[24:27], v[238:241], v[194:197], v[24:27]
	v_mfma_f32_16x16x32_bf16 v[20:23], v[238:241], v[198:201], v[20:23]
	v_mfma_f32_16x16x32_bf16 v[16:19], v[238:241], v[210:213], v[16:19]
	v_mfma_f32_16x16x32_bf16 v[12:15], v[242:245], v[190:193], v[12:15]
	v_mfma_f32_16x16x32_bf16 v[8:11], v[242:245], v[194:197], v[8:11]
	v_mfma_f32_16x16x32_bf16 v[4:7], v[242:245], v[198:201], v[4:7]
	v_mfma_f32_16x16x32_bf16 v[0:3], v[242:245], v[210:213], v[0:3]
	s_nop 15
	s_nop 15

.LBB0_1788:
	ds_read_b128 v[222:225], v159
	ds_read_b128 v[226:229], v160
	ds_read_b128 v[230:233], v161
	s_waitcnt lgkmcnt(5)
	v_mfma_f32_16x16x32_bf16 v[124:127], v[210:213], v[178:181], v[124:127]
	v_mfma_f32_16x16x32_bf16 v[120:123], v[210:213], v[182:185], v[120:123]
	v_mfma_f32_16x16x32_bf16 v[116:119], v[210:213], v[186:189], v[116:119]
	v_mfma_f32_16x16x32_bf16 v[112:115], v[210:213], v[190:193], v[112:115]
	ds_read_b128 v[234:237], v162
	s_waitcnt lgkmcnt(5)
	v_mfma_f32_16x16x32_bf16 v[108:111], v[214:217], v[178:181], v[108:111]
	v_mfma_f32_16x16x32_bf16 v[104:107], v[214:217], v[182:185], v[104:107]
	v_mfma_f32_16x16x32_bf16 v[100:103], v[214:217], v[186:189], v[100:103]
	v_mfma_f32_16x16x32_bf16 v[96:99], v[214:217], v[190:193], v[96:99]
	ds_read_b128 v[238:241], v163
	ds_read_b128 v[194:197], v155 offset:33792
	s_waitcnt lgkmcnt(6)
	v_mfma_f32_16x16x32_bf16 v[92:95], v[218:221], v[178:181], v[92:95]
	v_mfma_f32_16x16x32_bf16 v[88:91], v[218:221], v[182:185], v[88:91]
	v_mfma_f32_16x16x32_bf16 v[84:87], v[218:221], v[186:189], v[84:87]
	v_mfma_f32_16x16x32_bf16 v[80:83], v[218:221], v[190:193], v[80:83]
	ds_read_b128 v[210:213], v156 offset:1024
	ds_read_b128 v[198:201], v155 offset:35840
	s_waitcnt lgkmcnt(7)
	v_mfma_f32_16x16x32_bf16 v[76:79], v[222:225], v[178:181], v[76:79]
	v_mfma_f32_16x16x32_bf16 v[72:75], v[222:225], v[182:185], v[72:75]
	v_mfma_f32_16x16x32_bf16 v[68:71], v[222:225], v[186:189], v[68:71]
	v_mfma_f32_16x16x32_bf16 v[64:67], v[222:225], v[190:193], v[64:67]
	ds_read_b128 v[214:217], v157 offset:1024
	ds_read_b128 v[202:205], v155 offset:37888
	s_waitcnt lgkmcnt(8)
	v_mfma_f32_16x16x32_bf16 v[60:63], v[226:229], v[178:181], v[60:63]
	v_mfma_f32_16x16x32_bf16 v[56:59], v[226:229], v[182:185], v[56:59]
	v_mfma_f32_16x16x32_bf16 v[52:55], v[226:229], v[186:189], v[52:55]
	v_mfma_f32_16x16x32_bf16 v[48:51], v[226:229], v[190:193], v[48:51]
	ds_read_b128 v[218:221], v158 offset:1024
	ds_read_b128 v[206:209], v155 offset:39936
	s_waitcnt lgkmcnt(9)
	v_mfma_f32_16x16x32_bf16 v[44:47], v[230:233], v[178:181], v[44:47]
	v_mfma_f32_16x16x32_bf16 v[40:43], v[230:233], v[182:185], v[40:43]
	v_mfma_f32_16x16x32_bf16 v[36:39], v[230:233], v[186:189], v[36:39]
	v_mfma_f32_16x16x32_bf16 v[32:35], v[230:233], v[190:193], v[32:35]
	ds_read_b128 v[222:225], v159 offset:1024
	s_waitcnt lgkmcnt(9)
	v_mfma_f32_16x16x32_bf16 v[28:31], v[234:237], v[178:181], v[28:31]
	v_mfma_f32_16x16x32_bf16 v[24:27], v[234:237], v[182:185], v[24:27]
	v_mfma_f32_16x16x32_bf16 v[20:23], v[234:237], v[186:189], v[20:23]
	v_mfma_f32_16x16x32_bf16 v[16:19], v[234:237], v[190:193], v[16:19]
	ds_read_b128 v[226:229], v160 offset:1024
	s_waitcnt lgkmcnt(9)
	v_mfma_f32_16x16x32_bf16 v[12:15], v[238:241], v[178:181], v[12:15]
	v_mfma_f32_16x16x32_bf16 v[8:11], v[238:241], v[182:185], v[8:11]
	v_mfma_f32_16x16x32_bf16 v[4:7], v[238:241], v[186:189], v[4:7]
	v_mfma_f32_16x16x32_bf16 v[0:3], v[238:241], v[190:193], v[0:3]
	ds_read_b128 v[230:233], v161 offset:1024
	s_waitcnt lgkmcnt(3)
	v_mfma_f32_16x16x32_bf16 v[124:127], v[210:213], v[194:197], v[124:127]
	v_mfma_f32_16x16x32_bf16 v[120:123], v[210:213], v[198:201], v[120:123]
	v_mfma_f32_16x16x32_bf16 v[116:119], v[210:213], v[202:205], v[116:119]
	v_mfma_f32_16x16x32_bf16 v[112:115], v[210:213], v[206:209], v[112:115]
	ds_read_b128 v[234:237], v162 offset:1024
	v_mfma_f32_16x16x32_bf16 v[108:111], v[214:217], v[194:197], v[108:111]
	v_mfma_f32_16x16x32_bf16 v[104:107], v[214:217], v[198:201], v[104:107]
	v_mfma_f32_16x16x32_bf16 v[100:103], v[214:217], v[202:205], v[100:103]
	v_mfma_f32_16x16x32_bf16 v[96:99], v[214:217], v[206:209], v[96:99]
	ds_read_b128 v[238:241], v163 offset:1024
	v_mfma_f32_16x16x32_bf16 v[92:95], v[218:221], v[194:197], v[92:95]
	v_mfma_f32_16x16x32_bf16 v[88:91], v[218:221], v[198:201], v[88:91]
	v_mfma_f32_16x16x32_bf16 v[84:87], v[218:221], v[202:205], v[84:87]
	v_mfma_f32_16x16x32_bf16 v[80:83], v[218:221], v[206:209], v[80:83]
	s_waitcnt lgkmcnt(0)
	s_waitcnt vmcnt(0)
	s_barrier
	ds_read_b128 v[178:181], v164 offset:32768
	ds_read_b128 v[182:185], v164 offset:34816
	ds_read_b128 v[186:189], v164 offset:36864
	ds_read_b128 v[190:193], v164 offset:38912
	ds_read_b128 v[210:213], v172
	ds_read_b128 v[214:217], v173
	ds_read_b128 v[218:221], v165
	s_cmp_gt_u32 s1, 13
	s_cbranch_scc1 .Lg4_nostage0
	s_add_u32 m0, s45, 0x0
	v_mfma_f32_16x16x32_bf16 v[76:79], v[222:225], v[194:197], v[76:79]
	global_load_lds_dwordx4 v174, s[98:99]
	s_add_u32 m0, s45, 0x2000
	v_mfma_f32_16x16x32_bf16 v[72:75], v[222:225], v[198:201], v[72:75]
	global_load_lds_dwordx4 v175, s[98:99]
	v_mfma_f32_16x16x32_bf16 v[68:71], v[222:225], v[202:205], v[68:71]
	v_mfma_f32_16x16x32_bf16 v[64:67], v[222:225], v[206:209], v[64:67]
	s_add_u32 m0, s45, 0x4000
	v_mfma_f32_16x16x32_bf16 v[60:63], v[226:229], v[194:197], v[60:63]
	global_load_lds_dwordx4 v176, s[98:99]
	s_add_u32 m0, s45, 0x6000
	v_mfma_f32_16x16x32_bf16 v[56:59], v[226:229], v[198:201], v[56:59]
	global_load_lds_dwordx4 v177, s[98:99]
	v_mfma_f32_16x16x32_bf16 v[52:55], v[226:229], v[202:205], v[52:55]
	v_mfma_f32_16x16x32_bf16 v[48:51], v[226:229], v[206:209], v[48:51]
	s_add_u32 m0, s45, 0x8000
	v_mfma_f32_16x16x32_bf16 v[44:47], v[230:233], v[194:197], v[44:47]
	global_load_lds_dwordx4 v174, s[100:101]
	s_add_u32 m0, s45, 0xa000
	v_mfma_f32_16x16x32_bf16 v[40:43], v[230:233], v[198:201], v[40:43]
	global_load_lds_dwordx4 v175, s[100:101]
	v_mfma_f32_16x16x32_bf16 v[36:39], v[230:233], v[202:205], v[36:39]
	v_mfma_f32_16x16x32_bf16 v[32:35], v[230:233], v[206:209], v[32:35]
	s_add_u32 m0, s45, 0xc000
	v_mfma_f32_16x16x32_bf16 v[28:31], v[234:237], v[194:197], v[28:31]
	global_load_lds_dwordx4 v176, s[100:101]
	s_add_u32 m0, s45, 0xe000
	v_mfma_f32_16x16x32_bf16 v[24:27], v[234:237], v[198:201], v[24:27]
	global_load_lds_dwordx4 v177, s[100:101]
	v_mfma_f32_16x16x32_bf16 v[20:23], v[234:237], v[202:205], v[20:23]
	v_mfma_f32_16x16x32_bf16 v[16:19], v[234:237], v[206:209], v[16:19]
	v_mfma_f32_16x16x32_bf16 v[12:15], v[238:241], v[194:197], v[12:15]
	v_mfma_f32_16x16x32_bf16 v[8:11], v[238:241], v[198:201], v[8:11]
	v_mfma_f32_16x16x32_bf16 v[4:7], v[238:241], v[202:205], v[4:7]
	v_mfma_f32_16x16x32_bf16 v[0:3], v[238:241], v[206:209], v[0:3]
	s_add_u32 s98, s98, 0x80
	s_addc_u32 s99, s99, 0
	s_add_u32 s100, s100, 0x80
	s_addc_u32 s101, s101, 0
	s_branch .Lg4_half1
.Lg4_nostage0:
	v_mfma_f32_16x16x32_bf16 v[76:79], v[222:225], v[194:197], v[76:79]
	v_mfma_f32_16x16x32_bf16 v[72:75], v[222:225], v[198:201], v[72:75]
	v_mfma_f32_16x16x32_bf16 v[68:71], v[222:225], v[202:205], v[68:71]
	v_mfma_f32_16x16x32_bf16 v[64:67], v[222:225], v[206:209], v[64:67]
	v_mfma_f32_16x16x32_bf16 v[60:63], v[226:229], v[194:197], v[60:63]
	v_mfma_f32_16x16x32_bf16 v[56:59], v[226:229], v[198:201], v[56:59]
	v_mfma_f32_16x16x32_bf16 v[52:55], v[226:229], v[202:205], v[52:55]
	v_mfma_f32_16x16x32_bf16 v[48:51], v[226:229], v[206:209], v[48:51]
	v_mfma_f32_16x16x32_bf16 v[44:47], v[230:233], v[194:197], v[44:47]
	v_mfma_f32_16x16x32_bf16 v[40:43], v[230:233], v[198:201], v[40:43]
	v_mfma_f32_16x16x32_bf16 v[36:39], v[230:233], v[202:205], v[36:39]
	v_mfma_f32_16x16x32_bf16 v[32:35], v[230:233], v[206:209], v[32:35]
	v_mfma_f32_16x16x32_bf16 v[28:31], v[234:237], v[194:197], v[28:31]
	v_mfma_f32_16x16x32_bf16 v[24:27], v[234:237], v[198:201], v[24:27]
	v_mfma_f32_16x16x32_bf16 v[20:23], v[234:237], v[202:205], v[20:23]
	v_mfma_f32_16x16x32_bf16 v[16:19], v[234:237], v[206:209], v[16:19]
	v_mfma_f32_16x16x32_bf16 v[12:15], v[238:241], v[194:197], v[12:15]
	v_mfma_f32_16x16x32_bf16 v[8:11], v[238:241], v[198:201], v[8:11]
	v_mfma_f32_16x16x32_bf16 v[4:7], v[238:241], v[202:205], v[4:7]
	v_mfma_f32_16x16x32_bf16 v[0:3], v[238:241], v[206:209], v[0:3]
.Lg4_half1:
	ds_read_b128 v[222:225], v166
	ds_read_b128 v[226:229], v167
	ds_read_b128 v[230:233], v168
	s_waitcnt lgkmcnt(5)
	v_mfma_f32_16x16x32_bf16 v[124:127], v[210:213], v[178:181], v[124:127]
	v_mfma_f32_16x16x32_bf16 v[120:123], v[210:213], v[182:185], v[120:123]
	v_mfma_f32_16x16x32_bf16 v[116:119], v[210:213], v[186:189], v[116:119]
	v_mfma_f32_16x16x32_bf16 v[112:115], v[210:213], v[190:193], v[112:115]
	ds_read_b128 v[234:237], v169
	s_waitcnt lgkmcnt(5)
	v_mfma_f32_16x16x32_bf16 v[108:111], v[214:217], v[178:181], v[108:111]
	v_mfma_f32_16x16x32_bf16 v[104:107], v[214:217], v[182:185], v[104:107]
	v_mfma_f32_16x16x32_bf16 v[100:103], v[214:217], v[186:189], v[100:103]
	v_mfma_f32_16x16x32_bf16 v[96:99], v[214:217], v[190:193], v[96:99]
	ds_read_b128 v[238:241], v170
	ds_read_b128 v[194:197], v164 offset:33792
	s_waitcnt lgkmcnt(6)
	v_mfma_f32_16x16x32_bf16 v[92:95], v[218:221], v[178:181], v[92:95]
	v_mfma_f32_16x16x32_bf16 v[88:91], v[218:221], v[182:185], v[88:91]
	v_mfma_f32_16x16x32_bf16 v[84:87], v[218:221], v[186:189], v[84:87]
	v_mfma_f32_16x16x32_bf16 v[80:83], v[218:221], v[190:193], v[80:83]
	ds_read_b128 v[210:213], v172 offset:1024
	ds_read_b128 v[198:201], v164 offset:35840
	s_waitcnt lgkmcnt(7)
	v_mfma_f32_16x16x32_bf16 v[76:79], v[222:225], v[178:181], v[76:79]
	v_mfma_f32_16x16x32_bf16 v[72:75], v[222:225], v[182:185], v[72:75]
	v_mfma_f32_16x16x32_bf16 v[68:71], v[222:225], v[186:189], v[68:71]
	v_mfma_f32_16x16x32_bf16 v[64:67], v[222:225], v[190:193], v[64:67]
	ds_read_b128 v[214:217], v173 offset:1024
	ds_read_b128 v[202:205], v164 offset:37888
	s_waitcnt lgkmcnt(8)
	v_mfma_f32_16x16x32_bf16 v[60:63], v[226:229], v[178:181], v[60:63]
	v_mfma_f32_16x16x32_bf16 v[56:59], v[226:229], v[182:185], v[56:59]
	v_mfma_f32_16x16x32_bf16 v[52:55], v[226:229], v[186:189], v[52:55]
	v_mfma_f32_16x16x32_bf16 v[48:51], v[226:229], v[190:193], v[48:51]
	ds_read_b128 v[218:221], v165 offset:1024
	ds_read_b128 v[206:209], v164 offset:39936
	s_waitcnt lgkmcnt(9)
	v_mfma_f32_16x16x32_bf16 v[44:47], v[230:233], v[178:181], v[44:47]
	v_mfma_f32_16x16x32_bf16 v[40:43], v[230:233], v[182:185], v[40:43]
	v_mfma_f32_16x16x32_bf16 v[36:39], v[230:233], v[186:189], v[36:39]
	v_mfma_f32_16x16x32_bf16 v[32:35], v[230:233], v[190:193], v[32:35]
	ds_read_b128 v[222:225], v166 offset:1024
	s_waitcnt lgkmcnt(9)
	v_mfma_f32_16x16x32_bf16 v[28:31], v[234:237], v[178:181], v[28:31]
	v_mfma_f32_16x16x32_bf16 v[24:27], v[234:237], v[182:185], v[24:27]
	v_mfma_f32_16x16x32_bf16 v[20:23], v[234:237], v[186:189], v[20:23]
	v_mfma_f32_16x16x32_bf16 v[16:19], v[234:237], v[190:193], v[16:19]
	ds_read_b128 v[226:229], v167 offset:1024
	s_waitcnt lgkmcnt(9)
	v_mfma_f32_16x16x32_bf16 v[12:15], v[238:241], v[178:181], v[12:15]
	v_mfma_f32_16x16x32_bf16 v[8:11], v[238:241], v[182:185], v[8:11]
	v_mfma_f32_16x16x32_bf16 v[4:7], v[238:241], v[186:189], v[4:7]
	v_mfma_f32_16x16x32_bf16 v[0:3], v[238:241], v[190:193], v[0:3]
	ds_read_b128 v[230:233], v168 offset:1024
	s_waitcnt lgkmcnt(3)
	v_mfma_f32_16x16x32_bf16 v[124:127], v[210:213], v[194:197], v[124:127]
	v_mfma_f32_16x16x32_bf16 v[120:123], v[210:213], v[198:201], v[120:123]
	v_mfma_f32_16x16x32_bf16 v[116:119], v[210:213], v[202:205], v[116:119]
	v_mfma_f32_16x16x32_bf16 v[112:115], v[210:213], v[206:209], v[112:115]
	ds_read_b128 v[234:237], v169 offset:1024
	v_mfma_f32_16x16x32_bf16 v[108:111], v[214:217], v[194:197], v[108:111]
	v_mfma_f32_16x16x32_bf16 v[104:107], v[214:217], v[198:201], v[104:107]
	v_mfma_f32_16x16x32_bf16 v[100:103], v[214:217], v[202:205], v[100:103]
	v_mfma_f32_16x16x32_bf16 v[96:99], v[214:217], v[206:209], v[96:99]
	ds_read_b128 v[238:241], v170 offset:1024
	v_mfma_f32_16x16x32_bf16 v[92:95], v[218:221], v[194:197], v[92:95]
	v_mfma_f32_16x16x32_bf16 v[88:91], v[218:221], v[198:201], v[88:91]
	v_mfma_f32_16x16x32_bf16 v[84:87], v[218:221], v[202:205], v[84:87]
	v_mfma_f32_16x16x32_bf16 v[80:83], v[218:221], v[206:209], v[80:83]
	s_waitcnt lgkmcnt(0)
	s_waitcnt vmcnt(0)
	s_barrier
	s_cmp_gt_u32 s1, 13
	s_cbranch_scc1 .Lg4_last
	ds_read_b128 v[178:181], v155 offset:32768
	ds_read_b128 v[182:185], v155 offset:34816
	ds_read_b128 v[186:189], v155 offset:36864
	ds_read_b128 v[190:193], v155 offset:38912
	ds_read_b128 v[210:213], v156
	ds_read_b128 v[214:217], v157
	ds_read_b128 v[218:221], v158
	s_add_u32 m0, s45, 0x10400
	v_mfma_f32_16x16x32_bf16 v[76:79], v[222:225], v[194:197], v[76:79]
	global_load_lds_dwordx4 v174, s[98:99]
	s_add_u32 m0, s45, 0x12400
	v_mfma_f32_16x16x32_bf16 v[72:75], v[222:225], v[198:201], v[72:75]
	global_load_lds_dwordx4 v175, s[98:99]
	v_mfma_f32_16x16x32_bf16 v[68:71], v[222:225], v[202:205], v[68:71]
	v_mfma_f32_16x16x32_bf16 v[64:67], v[222:225], v[206:209], v[64:67]
	s_add_u32 m0, s45, 0x14400
	v_mfma_f32_16x16x32_bf16 v[60:63], v[226:229], v[194:197], v[60:63]
	global_load_lds_dwordx4 v176, s[98:99]
	s_add_u32 m0, s45, 0x16400
	v_mfma_f32_16x16x32_bf16 v[56:59], v[226:229], v[198:201], v[56:59]
	global_load_lds_dwordx4 v177, s[98:99]
	v_mfma_f32_16x16x32_bf16 v[52:55], v[226:229], v[202:205], v[52:55]
	v_mfma_f32_16x16x32_bf16 v[48:51], v[226:229], v[206:209], v[48:51]
	s_add_u32 m0, s45, 0x18400
	v_mfma_f32_16x16x32_bf16 v[44:47], v[230:233], v[194:197], v[44:47]
	global_load_lds_dwordx4 v174, s[100:101]
	s_add_u32 m0, s45, 0x1a400
	v_mfma_f32_16x16x32_bf16 v[40:43], v[230:233], v[198:201], v[40:43]
	global_load_lds_dwordx4 v175, s[100:101]
	v_mfma_f32_16x16x32_bf16 v[36:39], v[230:233], v[202:205], v[36:39]
	v_mfma_f32_16x16x32_bf16 v[32:35], v[230:233], v[206:209], v[32:35]
	s_add_u32 m0, s45, 0x1c400
	v_mfma_f32_16x16x32_bf16 v[28:31], v[234:237], v[194:197], v[28:31]
	global_load_lds_dwordx4 v176, s[100:101]
	s_add_u32 m0, s45, 0x1e400
	v_mfma_f32_16x16x32_bf16 v[24:27], v[234:237], v[198:201], v[24:27]
	global_load_lds_dwordx4 v177, s[100:101]
	v_mfma_f32_16x16x32_bf16 v[20:23], v[234:237], v[202:205], v[20:23]
	v_mfma_f32_16x16x32_bf16 v[16:19], v[234:237], v[206:209], v[16:19]
	v_mfma_f32_16x16x32_bf16 v[12:15], v[238:241], v[194:197], v[12:15]
	v_mfma_f32_16x16x32_bf16 v[8:11], v[238:241], v[198:201], v[8:11]
	v_mfma_f32_16x16x32_bf16 v[4:7], v[238:241], v[202:205], v[4:7]
	v_mfma_f32_16x16x32_bf16 v[0:3], v[238:241], v[206:209], v[0:3]
	s_add_u32 s98, s98, 0x80
	s_addc_u32 s99, s99, 0
	s_add_u32 s100, s100, 0x80
	s_addc_u32 s101, s101, 0
	s_add_i32 s1, s1, 2
	s_branch .LBB0_1788
.Lg4_last:
	v_mfma_f32_16x16x32_bf16 v[76:79], v[222:225], v[194:197], v[76:79]
	v_mfma_f32_16x16x32_bf16 v[72:75], v[222:225], v[198:201], v[72:75]
	v_mfma_f32_16x16x32_bf16 v[68:71], v[222:225], v[202:205], v[68:71]
	v_mfma_f32_16x16x32_bf16 v[64:67], v[222:225], v[206:209], v[64:67]
	v_mfma_f32_16x16x32_bf16 v[60:63], v[226:229], v[194:197], v[60:63]
	v_mfma_f32_16x16x32_bf16 v[56:59], v[226:229], v[198:201], v[56:59]
	v_mfma_f32_16x16x32_bf16 v[52:55], v[226:229], v[202:205], v[52:55]
	v_mfma_f32_16x16x32_bf16 v[48:51], v[226:229], v[206:209], v[48:51]
	v_mfma_f32_16x16x32_bf16 v[44:47], v[230:233], v[194:197], v[44:47]
	v_mfma_f32_16x16x32_bf16 v[40:43], v[230:233], v[198:201], v[40:43]
	v_mfma_f32_16x16x32_bf16 v[36:39], v[230:233], v[202:205], v[36:39]
	v_mfma_f32_16x16x32_bf16 v[32:35], v[230:233], v[206:209], v[32:35]
	v_mfma_f32_16x16x32_bf16 v[28:31], v[234:237], v[194:197], v[28:31]
	v_mfma_f32_16x16x32_bf16 v[24:27], v[234:237], v[198:201], v[24:27]
	v_mfma_f32_16x16x32_bf16 v[20:23], v[234:237], v[202:205], v[20:23]
	v_mfma_f32_16x16x32_bf16 v[16:19], v[234:237], v[206:209], v[16:19]
	v_mfma_f32_16x16x32_bf16 v[12:15], v[238:241], v[194:197], v[12:15]
	v_mfma_f32_16x16x32_bf16 v[8:11], v[238:241], v[198:201], v[8:11]
	v_mfma_f32_16x16x32_bf16 v[4:7], v[238:241], v[202:205], v[4:7]
	v_mfma_f32_16x16x32_bf16 v[0:3], v[238:241], v[206:209], v[0:3]
	s_nop 15
	s_nop 15
